# mLSTM: next-chunk raw q/k + V^T tile loads moved out of interval A clump and spread through step-4 MFMA code (dest reg holds own address); conv weights in LDS
# speedup vs baseline: 1.0064x; 1.0064x over previous
.LBB0_205:
	s_lshl_b32 s63, s12, 3
	s_lshl_b32 s3, s62, 1
	v_readlane_b32 s5, v252, 58
	s_add_u32 s46, s5, s3
	v_readlane_b32 s3, v252, 59
	s_addc_u32 s47, s3, 0
	s_lshr_b32 s13, s2, 7
	s_lshl_b32 s2, s12, 1
	s_and_b32 s14, s2, 2
	s_lshl_b32 s17, s13, 4
	s_lshl_b32 s2, s62, 2
	s_add_u32 s50, s68, s2
	s_addc_u32 s51, s69, 0
	s_add_i32 s2, s90, 0
	s_lshl_b32 s11, s12, 5
	s_add_i32 s2, s2, 0x18400
	s_or_b32 s92, s63, 1
	s_or_b32 s54, s63, 2
	s_or_b32 s5, s63, 3
	s_or_b32 s36, s63, 4
	s_or_b32 s35, s63, 5
	s_or_b32 s21, s63, 6
	s_or_b32 s20, s63, 7
	s_cmp_le_u32 s14, s13
	s_cselect_b64 s[52:53], -1, 0
	s_lshl_b32 s58, s14, 4
	s_lshl_b32 s59, s14, 5
	s_or_b32 s15, s14, 1
	s_cmp_ge_u32 s14, s13
	s_mov_b32 s13, s37
	s_mul_i32 s16, s12, 0x1080
	s_cselect_b64 s[90:91], -1, 0
	s_lshl_b32 s96, s15, 5
	s_lshl_b32 s97, s15, 4
	s_lshl_b64 s[14:15], s[82:83], 22
	s_lshl_b64 s[12:13], s[12:13], 14
	s_add_u32 s12, s14, s12
	s_addc_u32 s31, s15, s13
	s_lshl_b32 s4, s4, 9
	s_or_b32 s4, s12, s4
	s_lshl_b64 s[12:13], s[82:83], 12
	s_add_i32 s56, 0, 0x21800
	s_add_u32 s57, s12, 0xb000080
	v_mov_b32_e32 v0, 0
	s_mul_i32 s3, s92, 0x210
	s_addc_u32 s14, s13, 0
	s_mov_b64 s[82:83], 0
	v_mov_b32_e32 v1, v0
	v_mov_b32_e32 v2, v0
	v_mov_b32_e32 v3, v0
	v_mov_b32_e32 v4, v0
	v_mov_b32_e32 v5, v0
	v_mov_b32_e32 v6, v0
	v_mov_b32_e32 v7, v0
	v_mov_b32_e32 v8, v0
	v_mov_b32_e32 v9, v0
	v_mov_b32_e32 v10, v0
	v_mov_b32_e32 v11, v0
	v_mov_b32_e32 v12, v0
	v_mov_b32_e32 v13, v0
	v_mov_b32_e32 v14, v0
	v_mov_b32_e32 v15, v0
	v_mov_b32_e32 v16, v0
	v_mov_b32_e32 v17, v0
	v_mov_b32_e32 v18, v0
	v_mov_b32_e32 v19, v0
	v_mov_b32_e32 v20, v0
	v_mov_b32_e32 v21, v0
	v_mov_b32_e32 v22, v0
	v_mov_b32_e32 v23, v0
	v_mov_b32_e32 v24, v0
	v_mov_b32_e32 v25, v0
	v_mov_b32_e32 v26, v0
	v_mov_b32_e32 v27, v0
	v_mov_b32_e32 v28, v0
	v_mov_b32_e32 v29, v0
	v_mov_b32_e32 v30, v0
	v_mov_b32_e32 v31, v0
	v_mov_b32_e32 v32, v0
	v_mov_b32_e32 v33, v0
	v_mov_b32_e32 v34, v0
	v_mov_b32_e32 v35, v0
	v_mov_b32_e32 v36, v0
	v_mov_b32_e32 v37, v0
	v_mov_b32_e32 v38, v0
	v_mov_b32_e32 v39, v0
	v_mov_b32_e32 v40, v0
	v_mov_b32_e32 v41, v0
	v_mov_b32_e32 v42, v0
	v_mov_b32_e32 v43, v0
	v_mov_b32_e32 v44, v0
	v_mov_b32_e32 v45, v0
	v_mov_b32_e32 v46, v0
	v_mov_b32_e32 v47, v0
	v_mov_b32_e32 v48, v0
	v_mov_b32_e32 v49, v0
	v_mov_b32_e32 v50, v0
	v_mov_b32_e32 v51, v0
	v_mov_b32_e32 v52, v0
	v_mov_b32_e32 v53, v0
	v_mov_b32_e32 v54, v0
	v_mov_b32_e32 v55, v0
	v_mov_b32_e32 v56, v0
	v_mov_b32_e32 v57, v0
	v_mov_b32_e32 v58, v0
	v_mov_b32_e32 v59, v0
	v_mov_b32_e32 v60, v0
	v_mov_b32_e32 v61, v0
	v_mov_b32_e32 v62, v0
	v_mov_b32_e32 v63, v0
	s_waitcnt vmcnt(0)
	s_branch .LBB0_207

.LBB0_207:
	v_mov_b32_e32 v214, v222
	v_mov_b32_e32 v64, s56
	ds_read2_b32 v[164:165], v64 offset0:32 offset1:64
	v_cndmask_b32_e64 v64, 0, 1, s[48:49]
	v_cmp_ne_u32_e64 s[42:43], 1, v64
	s_andn2_b64 vcc, exec, s[48:49]
	v_and_b32_e32 v168, 63, v214
	s_cbranch_vccnz .LBB0_211
	v_mov_b32_e32 v64, s56
	ds_read_b32 v64, v64
	v_lshl_add_u32 v67, v168, 2, 0
	s_waitcnt vmcnt(4) lgkmcnt(2)
	v_add_f32_e32 v66, v213, v98
	v_add_u32_e32 v68, 0x20800, v67
	ds_write_b32 v68, v213
	s_waitcnt lgkmcnt(1)
	v_add_f32_e32 v65, v213, v64
	v_max_f32_e32 v66, v65, v66
	v_add_u32_e32 v68, 0x20900, v67
	ds_write_b32 v68, v99
	v_add_u32_e32 v68, 0x20a00, v67
	v_sub_f32_e32 v65, v65, v66
	ds_write_b32 v68, v66
	v_mul_f32_e32 v68, 0x3fb8aa3b, v65
	v_fma_f32 v69, v65, s0, -v68
	v_rndne_f32_e32 v70, v68
	v_fmac_f32_e32 v69, 0x32a5705f, v65
	v_sub_f32_e32 v68, v68, v70
	v_add_f32_e32 v68, v68, v69
	v_exp_f32_e32 v68, v68
	v_cvt_i32_f32_e32 v69, v70
	v_cmp_ngt_f32_e32 vcc, s28, v65
	v_ldexp_f32 v68, v68, v69
	s_nop 0
	v_cndmask_b32_e32 v68, 0, v68, vcc
	v_cmp_nlt_f32_e32 vcc, s29, v65
	s_nop 1
	v_cndmask_b32_e32 v65, v229, v68, vcc
	v_add_u32_e32 v68, 0x20b00, v67
	ds_write_b32 v68, v65
	v_mul_f32_e32 v65, 0xbfb8aa3b, v66
	v_fma_f32 v68, v66, s94, -v65
	v_rndne_f32_e32 v69, v65
	v_fmac_f32_e32 v68, 0xb2a5705f, v66
	v_sub_f32_e32 v65, v65, v69
	v_add_f32_e32 v65, v65, v68
	v_exp_f32_e32 v65, v65
	v_cvt_i32_f32_e32 v68, v69
	v_cmp_nlt_f32_e32 vcc, s22, v66
	v_ldexp_f32 v65, v65, v68
	s_nop 0
	v_cndmask_b32_e32 v65, 0, v65, vcc
	v_cmp_ngt_f32_e32 vcc, s23, v66
	v_add_u32_e32 v66, 0x20f00, v67
	s_nop 0
	v_cndmask_b32_e32 v65, v229, v65, vcc
	v_cmp_eq_u32_e32 vcc, 0, v168
	ds_write_b32 v66, v65
	s_and_saveexec_b64 s[12:13], vcc
	s_cbranch_execz .LBB0_210
	v_add_f32_e32 v64, v165, v64
	v_sub_f32_e32 v64, v64, v164
	v_mul_f32_e32 v65, 0x3fb8aa3b, v64
	v_fma_f32 v66, v64, s0, -v65
	v_rndne_f32_e32 v67, v65
	v_fmac_f32_e32 v66, 0x32a5705f, v64
	v_sub_f32_e32 v65, v65, v67
	v_add_f32_e32 v65, v65, v66
	v_cvt_i32_f32_e32 v66, v67
	v_exp_f32_e32 v65, v65
	v_cmp_ngt_f32_e32 vcc, s28, v64
	v_ldexp_f32 v65, v65, v66
	s_nop 0
	v_cndmask_b32_e32 v65, 0, v65, vcc
	v_cmp_nlt_f32_e32 vcc, s29, v64
	s_nop 1
	v_cndmask_b32_e32 v64, v229, v65, vcc
	v_mov_b32_e32 v65, s10
	ds_write_b32 v65, v64

.LBB0_211:
	v_and_b32_e32 v215, 31, v214
	v_lshlrev_b32_e32 v64, 3, v215
	v_add_u32_e32 v65, s33, v64
	v_or_b32_e32 v64, s55, v64
	v_cmp_lt_u32_e64 s[44:45], 15, v215
	s_movk_i32 s12, 0x2000
	s_waitcnt vmcnt(4)
	v_lshlrev_b32_e32 v166, 16, v104
	v_cndmask_b32_e64 v169, v64, v65, s[44:45]
	v_lshlrev_b32_e32 v96, 2, v169
	v_lshlrev_b32_e32 v171, 4, v215
	v_add_u32_e32 v171, 0x21a00, v171
	v_and_b32_e32 v167, 0xffff0000, v104
	s_mov_b64 s[12:13], 0x3000
	ds_read_b128 v[84:87], v171 offset:1024
	ds_read_b128 v[88:91], v171
	ds_read_b128 v[92:95], v171 offset:4096
	ds_read_b128 v[156:159], v171 offset:2048
	ds_read_b128 v[160:163], v171 offset:3072
	ds_read_b128 v[64:67], v171 offset:512
	ds_read_b128 v[68:71], v171 offset:4608
	ds_read_b128 v[72:75], v171 offset:1536
	ds_read_b128 v[76:79], v171 offset:2560
	ds_read_b128 v[80:83], v171 offset:3584
	v_lshlrev_b32_e32 v172, 16, v100
	v_and_b32_e32 v173, 0xffff0000, v100
	v_lshlrev_b32_e32 v174, 16, v108
	v_and_b32_e32 v175, 0xffff0000, v108
	v_lshlrev_b32_e32 v176, 16, v112
	v_and_b32_e32 v177, 0xffff0000, v112
	v_lshlrev_b32_e32 v178, 16, v116
	v_and_b32_e32 v179, 0xffff0000, v116
	v_lshlrev_b32_e32 v180, 16, v120
	v_and_b32_e32 v181, 0xffff0000, v120
	v_lshlrev_b32_e32 v182, 16, v124
	v_and_b32_e32 v183, 0xffff0000, v124
	v_ashrrev_i32_e32 v170, 5, v214
	s_movk_i32 s12, 0x440
	v_cmp_gt_u32_e32 vcc, 16, v215
	s_waitcnt lgkmcnt(7)
	v_pk_fma_f32 v[166:167], v[88:89], v[166:167], v[92:93]
	v_pk_fma_f32 v[184:185], v[88:89], v[172:173], v[92:93]
	v_pk_fma_f32 v[186:187], v[88:89], v[174:175], v[92:93]
	v_pk_fma_f32 v[88:89], v[88:89], v[176:177], v[92:93]
	v_pk_fma_f32 v[92:93], v[84:85], v[172:173], v[166:167]
	v_pk_fma_f32 v[166:167], v[84:85], v[174:175], v[184:185]
	v_pk_fma_f32 v[172:173], v[84:85], v[176:177], v[186:187]
	v_pk_fma_f32 v[84:85], v[84:85], v[178:179], v[88:89]
	s_waitcnt lgkmcnt(6)
	v_pk_fma_f32 v[88:89], v[156:157], v[174:175], v[92:93]
	v_pk_fma_f32 v[92:93], v[156:157], v[176:177], v[166:167]
	v_pk_fma_f32 v[166:167], v[156:157], v[178:179], v[172:173]
	v_pk_fma_f32 v[84:85], v[156:157], v[180:181], v[84:85]
	s_waitcnt lgkmcnt(5)
	v_pk_fma_f32 v[88:89], v[160:161], v[176:177], v[88:89]
	v_pk_fma_f32 v[156:157], v[160:161], v[178:179], v[92:93]
	v_pk_fma_f32 v[166:167], v[160:161], v[180:181], v[166:167]
	v_pk_fma_f32 v[160:161], v[160:161], v[182:183], v[84:85]
	v_mul_f32_e32 v84, 0xbfb8aa3b, v88
	v_mul_f32_e32 v85, 0xbfb8aa3b, v89
	v_mul_f32_e32 v92, 0xbfb8aa3b, v156
	v_mul_f32_e32 v93, 0xbfb8aa3b, v157
	v_mul_f32_e32 v96, 0xbfb8aa3b, v166
	v_mul_f32_e32 v171, 0xbfb8aa3b, v167
	v_mul_f32_e32 v172, 0xbfb8aa3b, v160
	v_mul_f32_e32 v173, 0xbfb8aa3b, v161
	v_exp_f32_e32 v84, v84
	v_exp_f32_e32 v85, v85
	v_exp_f32_e32 v92, v92
	v_exp_f32_e32 v93, v93
	v_exp_f32_e32 v96, v96
	v_exp_f32_e32 v171, v171
	v_exp_f32_e32 v172, v172
	v_exp_f32_e32 v173, v173
	v_add_f32_e32 v84, 1.0, v84
	v_add_f32_e32 v85, 1.0, v85
	v_add_f32_e32 v92, 1.0, v92
	v_add_f32_e32 v93, 1.0, v93
	v_add_f32_e32 v96, 1.0, v96
	v_add_f32_e32 v171, 1.0, v171
	v_add_f32_e32 v176, 1.0, v172
	v_add_f32_e32 v177, 1.0, v173
	v_rcp_f32_e32 v84, v84
	v_rcp_f32_e32 v85, v85
	v_rcp_f32_e32 v172, v92
	v_rcp_f32_e32 v173, v93
	v_rcp_f32_e32 v174, v96
	v_rcp_f32_e32 v175, v171
	v_pk_mul_f32 v[92:93], v[88:89], v[84:85]
	v_pk_mul_f32 v[88:89], v[156:157], v[172:173]
	v_lshlrev_b32_e32 v156, 16, v105
	v_and_b32_e32 v157, 0xffff0000, v105
	v_pk_mul_f32 v[84:85], v[166:167], v[174:175]
	v_lshlrev_b32_e32 v166, 16, v101
	v_and_b32_e32 v167, 0xffff0000, v101
	v_pk_fma_f32 v[156:157], v[90:91], v[156:157], v[94:95]
	v_lshlrev_b32_e32 v172, 16, v109
	v_and_b32_e32 v173, 0xffff0000, v109
	v_pk_fma_f32 v[156:157], v[86:87], v[166:167], v[156:157]
	v_lshlrev_b32_e32 v174, 16, v113
	v_and_b32_e32 v175, 0xffff0000, v113
	v_pk_fma_f32 v[156:157], v[158:159], v[172:173], v[156:157]
	v_rcp_f32_e32 v176, v176
	v_pk_fma_f32 v[178:179], v[162:163], v[174:175], v[156:157]
	v_rcp_f32_e32 v177, v177
	v_mul_f32_e32 v96, 0xbfb8aa3b, v178
	v_exp_f32_e32 v96, v96
	v_mul_f32_e32 v156, 0xbfb8aa3b, v179
	v_exp_f32_e32 v171, v156
	v_pk_fma_f32 v[166:167], v[90:91], v[166:167], v[94:95]
	v_pk_mul_f32 v[156:157], v[160:161], v[176:177]
	v_pk_fma_f32 v[166:167], v[86:87], v[172:173], v[166:167]
	v_add_f32_e32 v96, 1.0, v96
	v_lshlrev_b32_e32 v176, 16, v117
	v_and_b32_e32 v177, 0xffff0000, v117
	v_pk_fma_f32 v[166:167], v[158:159], v[174:175], v[166:167]
	v_rcp_f32_e32 v160, v96
	v_add_f32_e32 v96, 1.0, v171
	v_pk_fma_f32 v[166:167], v[162:163], v[176:177], v[166:167]
	v_rcp_f32_e32 v161, v96
	v_mul_f32_e32 v96, 0xbfb8aa3b, v166
	v_exp_f32_e32 v96, v96
	v_mul_f32_e32 v171, 0xbfb8aa3b, v167
	v_exp_f32_e32 v171, v171
	v_pk_fma_f32 v[172:173], v[90:91], v[172:173], v[94:95]
	v_add_f32_e32 v96, 1.0, v96
	v_pk_fma_f32 v[172:173], v[86:87], v[174:175], v[172:173]
	v_lshlrev_b32_e32 v180, 16, v121
	v_and_b32_e32 v181, 0xffff0000, v121
	v_pk_fma_f32 v[172:173], v[158:159], v[176:177], v[172:173]
	v_pk_mul_f32 v[160:161], v[178:179], v[160:161]
	v_rcp_f32_e32 v178, v96
	v_add_f32_e32 v96, 1.0, v171
	v_pk_fma_f32 v[172:173], v[162:163], v[180:181], v[172:173]
	v_rcp_f32_e32 v179, v96
	v_mul_f32_e32 v96, 0xbfb8aa3b, v172
	v_exp_f32_e32 v96, v96
	v_mul_f32_e32 v171, 0xbfb8aa3b, v173
	v_exp_f32_e32 v171, v171
	v_pk_fma_f32 v[90:91], v[90:91], v[174:175], v[94:95]
	v_add_f32_e32 v96, 1.0, v96
	v_pk_fma_f32 v[86:87], v[86:87], v[176:177], v[90:91]
	v_pk_mul_f32 v[166:167], v[166:167], v[178:179]
	v_rcp_f32_e32 v178, v96
	v_add_f32_e32 v96, 1.0, v171
	v_lshlrev_b32_e32 v182, 16, v125
	v_and_b32_e32 v183, 0xffff0000, v125
	v_pk_fma_f32 v[86:87], v[158:159], v[180:181], v[86:87]
	v_rcp_f32_e32 v179, v96
	v_pk_fma_f32 v[90:91], v[162:163], v[182:183], v[86:87]
	v_lshlrev_b32_e32 v158, 16, v106
	v_mul_f32_e32 v86, 0xbfb8aa3b, v90
	v_exp_f32_e32 v94, v86
	v_mul_f32_e32 v86, 0xbfb8aa3b, v91
	v_and_b32_e32 v159, 0xffff0000, v106
	v_exp_f32_e32 v95, v86
	v_lshlrev_b32_e32 v162, 16, v102
	v_and_b32_e32 v163, 0xffff0000, v102
	s_waitcnt lgkmcnt(3)
	v_pk_fma_f32 v[158:159], v[64:65], v[158:159], v[68:69]
	v_pk_mul_f32 v[86:87], v[172:173], v[178:179]
	v_lshlrev_b32_e32 v172, 16, v110
	v_and_b32_e32 v173, 0xffff0000, v110
	s_waitcnt lgkmcnt(2)
	v_pk_fma_f32 v[158:159], v[72:73], v[162:163], v[158:159]
	v_lshlrev_b32_e32 v174, 16, v114
	v_and_b32_e32 v175, 0xffff0000, v114
	s_waitcnt lgkmcnt(1)
	v_pk_fma_f32 v[158:159], v[76:77], v[172:173], v[158:159]
	v_add_f32_e32 v94, 1.0, v94
	s_waitcnt lgkmcnt(0)
	v_pk_fma_f32 v[158:159], v[80:81], v[174:175], v[158:159]
	v_add_f32_e32 v95, 1.0, v95
	v_mul_f32_e32 v96, 0xbfb8aa3b, v158
	v_rcp_f32_e32 v94, v94
	v_rcp_f32_e32 v95, v95
	v_exp_f32_e32 v96, v96
	v_mul_f32_e32 v171, 0xbfb8aa3b, v159
	v_pk_fma_f32 v[162:163], v[64:65], v[162:163], v[68:69]
	v_exp_f32_e32 v171, v171
	v_pk_fma_f32 v[162:163], v[72:73], v[172:173], v[162:163]
	v_lshlrev_b32_e32 v176, 16, v118
	v_and_b32_e32 v177, 0xffff0000, v118
	v_pk_fma_f32 v[162:163], v[76:77], v[174:175], v[162:163]
	v_pk_mul_f32 v[90:91], v[90:91], v[94:95]
	v_pk_fma_f32 v[162:163], v[80:81], v[176:177], v[162:163]
	v_add_f32_e32 v94, 1.0, v96
	v_mul_f32_e32 v96, 0xbfb8aa3b, v162
	v_add_f32_e32 v95, 1.0, v171
	v_exp_f32_e32 v96, v96
	v_mul_f32_e32 v171, 0xbfb8aa3b, v163
	v_rcp_f32_e32 v94, v94
	v_rcp_f32_e32 v95, v95
	v_exp_f32_e32 v171, v171
	v_pk_fma_f32 v[172:173], v[64:65], v[172:173], v[68:69]
	v_add_f32_e32 v96, 1.0, v96
	v_pk_fma_f32 v[172:173], v[72:73], v[174:175], v[172:173]
	v_lshlrev_b32_e32 v178, 16, v122
	v_and_b32_e32 v179, 0xffff0000, v122
	v_pk_fma_f32 v[172:173], v[76:77], v[176:177], v[172:173]
	v_pk_mul_f32 v[94:95], v[158:159], v[94:95]
	v_rcp_f32_e32 v158, v96
	v_add_f32_e32 v96, 1.0, v171
	v_pk_fma_f32 v[172:173], v[80:81], v[178:179], v[172:173]
	v_rcp_f32_e32 v159, v96
	v_mul_f32_e32 v96, 0xbfb8aa3b, v172
	v_exp_f32_e32 v96, v96
	v_mul_f32_e32 v171, 0xbfb8aa3b, v173
	v_exp_f32_e32 v171, v171
	v_pk_fma_f32 v[64:65], v[64:65], v[174:175], v[68:69]
	v_add_f32_e32 v96, 1.0, v96
	v_pk_fma_f32 v[64:65], v[72:73], v[176:177], v[64:65]
	v_lshlrev_b32_e32 v180, 16, v126
	v_and_b32_e32 v181, 0xffff0000, v126
	v_pk_fma_f32 v[64:65], v[76:77], v[178:179], v[64:65]
	v_pk_mul_f32 v[158:159], v[162:163], v[158:159]
	v_rcp_f32_e32 v162, v96
	v_add_f32_e32 v96, 1.0, v171
	v_pk_fma_f32 v[64:65], v[80:81], v[180:181], v[64:65]
	v_rcp_f32_e32 v163, v96
	v_mul_f32_e32 v68, 0xbfb8aa3b, v64
	v_mul_f32_e32 v69, 0xbfb8aa3b, v65
	v_exp_f32_e32 v68, v68
	v_exp_f32_e32 v69, v69
	v_lshlrev_b32_e32 v72, 16, v107
	v_and_b32_e32 v73, 0xffff0000, v107
	v_lshlrev_b32_e32 v80, 16, v103
	v_and_b32_e32 v81, 0xffff0000, v103
	v_pk_fma_f32 v[72:73], v[66:67], v[72:73], v[70:71]
	v_pk_mul_f32 v[76:77], v[172:173], v[162:163]
	v_lshlrev_b32_e32 v162, 16, v111
	v_and_b32_e32 v163, 0xffff0000, v111
	v_pk_fma_f32 v[72:73], v[74:75], v[80:81], v[72:73]
	v_add_f32_e32 v68, 1.0, v68
	v_add_f32_e32 v69, 1.0, v69
	v_lshlrev_b32_e32 v172, 16, v115
	v_and_b32_e32 v173, 0xffff0000, v115
	v_pk_fma_f32 v[72:73], v[78:79], v[162:163], v[72:73]
	v_rcp_f32_e32 v68, v68
	v_rcp_f32_e32 v69, v69
	v_pk_fma_f32 v[174:175], v[82:83], v[172:173], v[72:73]
	v_pk_fma_f32 v[80:81], v[66:67], v[80:81], v[70:71]
	v_mul_f32_e32 v72, 0xbfb8aa3b, v174
	v_exp_f32_e32 v96, v72
	v_mul_f32_e32 v72, 0xbfb8aa3b, v175
	v_exp_f32_e32 v171, v72
	v_pk_fma_f32 v[80:81], v[74:75], v[162:163], v[80:81]
	v_pk_mul_f32 v[72:73], v[64:65], v[68:69]
	v_lshlrev_b32_e32 v68, 16, v119
	v_and_b32_e32 v69, 0xffff0000, v119
	v_pk_fma_f32 v[80:81], v[78:79], v[172:173], v[80:81]
	v_add_f32_e32 v64, 1.0, v96
	v_pk_fma_f32 v[80:81], v[82:83], v[68:69], v[80:81]
	v_add_f32_e32 v65, 1.0, v171
	v_mul_f32_e32 v96, 0xbfb8aa3b, v80
	v_exp_f32_e32 v96, v96
	v_mul_f32_e32 v171, 0xbfb8aa3b, v81
	v_pk_fma_f32 v[162:163], v[66:67], v[162:163], v[70:71]
	v_pk_fma_f32 v[66:67], v[66:67], v[172:173], v[70:71]
	v_exp_f32_e32 v171, v171
	v_lshlrev_b32_e32 v178, 16, v123
	v_and_b32_e32 v179, 0xffff0000, v123
	v_pk_fma_f32 v[66:67], v[74:75], v[68:69], v[66:67]
	v_pk_fma_f32 v[162:163], v[74:75], v[172:173], v[162:163]
	v_lshlrev_b32_e32 v182, 16, v127
	v_and_b32_e32 v183, 0xffff0000, v127
	v_pk_fma_f32 v[66:67], v[78:79], v[178:179], v[66:67]
	v_pk_fma_f32 v[162:163], v[78:79], v[68:69], v[162:163]
	v_pk_fma_f32 v[74:75], v[82:83], v[182:183], v[66:67]
	v_add_f32_e32 v96, 1.0, v96
	v_pk_fma_f32 v[162:163], v[82:83], v[178:179], v[162:163]
	v_mul_f32_e32 v66, 0xbfb8aa3b, v74
	v_rcp_f32_e32 v176, v96
	v_add_f32_e32 v96, 1.0, v171
	v_mul_f32_e32 v171, 0xbfb8aa3b, v162
	v_exp_f32_e32 v66, v66
	v_mul_f32_e32 v67, 0xbfb8aa3b, v75
	v_exp_f32_e32 v171, v171
	v_mul_f32_e32 v177, 0xbfb8aa3b, v163
	v_exp_f32_e32 v67, v67
	v_exp_f32_e32 v181, v177
	v_add_f32_e32 v66, 1.0, v66
	v_rcp_f32_e32 v177, v96
	v_add_f32_e32 v96, 1.0, v171
	v_rcp_f32_e32 v78, v66
	v_add_f32_e32 v66, 1.0, v67
	v_rcp_f32_e32 v64, v64
	v_rcp_f32_e32 v65, v65
	v_rcp_f32_e32 v180, v96
	v_add_f32_e32 v96, 1.0, v181
	v_rcp_f32_e32 v79, v66
	v_rcp_f32_e32 v181, v96
	v_pk_mul_f32 v[70:71], v[174:175], v[64:65]
	v_pk_mul_f32 v[68:69], v[80:81], v[176:177]
	v_pk_mul_f32 v[64:65], v[74:75], v[78:79]
	v_lshlrev_b32_e32 v74, 4, v215
	v_mul_lo_u32 v75, v170, s12
	v_pk_mul_f32 v[66:67], v[162:163], v[180:181]
	v_add3_u32 v96, 0, v74, v75
	s_and_saveexec_b64 s[12:13], vcc
	s_xor_b64 s[12:13], exec, s[12:13]
	s_cbranch_execz .LBB0_213
	v_cvt_pk_bf16_f32 v78, v92, v93
	v_cvt_pk_bf16_f32 v79, v160, v161
	v_cvt_pk_bf16_f32 v80, v94, v95
	v_cvt_pk_bf16_f32 v81, v70, v71
	ds_write_b128 v96, v[78:81]
	v_cvt_pk_bf16_f32 v81, v68, v69
	v_cvt_pk_bf16_f32 v68, v84, v85
	v_cvt_pk_bf16_f32 v69, v86, v87
	v_cvt_pk_bf16_f32 v70, v76, v77
	v_cvt_pk_bf16_f32 v71, v66, v67
	v_cvt_pk_bf16_f32 v78, v88, v89
	v_cvt_pk_bf16_f32 v79, v166, v167
	v_cvt_pk_bf16_f32 v80, v158, v159
	ds_write_b128 v96, v[68:71] offset:544
	v_cvt_pk_bf16_f32 v66, v156, v157
	v_cvt_pk_bf16_f32 v67, v90, v91
	v_cvt_pk_bf16_f32 v68, v72, v73
	v_cvt_pk_bf16_f32 v69, v64, v65
	ds_write_b128 v96, v[78:81] offset:272
	ds_write_b128 v96, v[66:69] offset:816
.LBB0_213:
	s_andn2_saveexec_b64 s[12:13], s[12:13]
	s_cbranch_execz .LBB0_215
	v_pk_mul_f32 v[70:71], v[70:71], s[24:25] op_sel_hi:[1,0]
	v_pk_mul_f32 v[78:79], v[94:95], s[24:25] op_sel_hi:[1,0]
	v_pk_mul_f32 v[80:81], v[90:91], s[24:25] op_sel_hi:[1,0]
	v_pk_mul_f32 v[90:91], v[160:161], s[24:25] op_sel_hi:[1,0]
	v_pk_mul_f32 v[92:93], v[92:93], s[24:25] op_sel_hi:[1,0]
	v_pk_mul_f32 v[68:69], v[68:69], s[24:25] op_sel_hi:[1,0]
	v_pk_mul_f32 v[74:75], v[76:77], s[24:25] op_sel_hi:[1,0]
	v_pk_mul_f32 v[76:77], v[158:159], s[24:25] op_sel_hi:[1,0]
	v_pk_mul_f32 v[82:83], v[86:87], s[24:25] op_sel_hi:[1,0]
	v_pk_mul_f32 v[86:87], v[166:167], s[24:25] op_sel_hi:[1,0]
	v_pk_mul_f32 v[94:95], v[156:157], s[24:25] op_sel_hi:[1,0]
	v_pk_mul_f32 v[88:89], v[88:89], s[24:25] op_sel_hi:[1,0]
	v_cvt_pk_bf16_f32 v156, v92, v93
	v_cvt_pk_bf16_f32 v157, v90, v91
	v_cvt_pk_bf16_f32 v158, v78, v79
	v_cvt_pk_bf16_f32 v159, v70, v71
	v_pk_mul_f32 v[66:67], v[66:67], s[24:25] op_sel_hi:[1,0]
	v_pk_mul_f32 v[84:85], v[84:85], s[24:25] op_sel_hi:[1,0]
	ds_write_b128 v96, v[156:159] offset:17152
	v_cvt_pk_bf16_f32 v156, v88, v89
	v_cvt_pk_bf16_f32 v157, v86, v87
	v_cvt_pk_bf16_f32 v158, v76, v77
	v_cvt_pk_bf16_f32 v159, v68, v69
	v_pk_mul_f32 v[64:65], v[64:65], s[24:25] op_sel_hi:[1,0]
	v_pk_mul_f32 v[72:73], v[72:73], s[24:25] op_sel_hi:[1,0]
	ds_write_b128 v96, v[156:159] offset:17424
	v_cvt_pk_bf16_f32 v156, v84, v85
	v_cvt_pk_bf16_f32 v157, v82, v83
	v_cvt_pk_bf16_f32 v158, v74, v75
	v_cvt_pk_bf16_f32 v159, v66, v67
	ds_write_b128 v96, v[156:159] offset:17696
	v_cvt_pk_bf16_f32 v156, v94, v95
	v_cvt_pk_bf16_f32 v157, v80, v81
	v_cvt_pk_bf16_f32 v158, v72, v73
	v_cvt_pk_bf16_f32 v159, v64, v65
	ds_write_b128 v96, v[156:159] offset:17968
	s_waitcnt vmcnt(0) lgkmcnt(4)
	v_sub_f32_e32 v96, v165, v132
	v_add_f32_e32 v96, v136, v96
	v_sub_f32_e32 v96, v96, v164
	v_mul_f32_e32 v156, 0x3fb8aa3b, v96
	v_fma_f32 v157, v96, s0, -v156
	v_rndne_f32_e32 v158, v156
	v_fmac_f32_e32 v157, 0x32a5705f, v96
	v_sub_f32_e32 v156, v156, v158
	v_add_f32_e32 v156, v156, v157
	v_exp_f32_e32 v156, v156
	v_cvt_i32_f32_e32 v157, v158
	v_cmp_ngt_f32_e32 vcc, s28, v96
	v_mov_b32_e32 v162, v84
	v_mov_b32_e32 v163, v94
	v_ldexp_f32 v156, v156, v157
	v_cndmask_b32_e32 v156, 0, v156, vcc
	v_cmp_nlt_f32_e32 vcc, s29, v96
	v_sub_f32_e32 v96, v165, v133
	v_add_f32_e32 v96, v137, v96
	v_sub_f32_e32 v96, v96, v164
	v_mul_f32_e32 v157, 0x3fb8aa3b, v96
	v_fma_f32 v158, v96, s0, -v157
	v_rndne_f32_e32 v159, v157
	v_fmac_f32_e32 v158, 0x32a5705f, v96
	v_sub_f32_e32 v157, v157, v159
	v_add_f32_e32 v157, v157, v158
	v_exp_f32_e32 v157, v157
	v_cvt_i32_f32_e32 v158, v159
	v_cndmask_b32_e32 v156, v229, v156, vcc
	v_cmp_ngt_f32_e32 vcc, s28, v96
	v_mul_u32_u24_e32 v84, 0x480, v215
	v_ldexp_f32 v157, v157, v158
	v_cndmask_b32_e32 v157, 0, v157, vcc
	v_cmp_nlt_f32_e32 vcc, s29, v96
	v_sub_f32_e32 v96, v165, v134
	v_add_f32_e32 v96, v138, v96
	v_sub_f32_e32 v96, v96, v164
	v_mul_f32_e32 v158, 0x3fb8aa3b, v96
	v_fma_f32 v159, v96, s0, -v158
	v_rndne_f32_e32 v160, v158
	v_fmac_f32_e32 v159, 0x32a5705f, v96
	v_sub_f32_e32 v158, v158, v160
	v_add_f32_e32 v158, v158, v159
	v_exp_f32_e32 v158, v158
	v_cvt_i32_f32_e32 v159, v160
	v_cndmask_b32_e32 v157, v229, v157, vcc
	v_cmp_ngt_f32_e32 vcc, s28, v96
	v_mov_b32_e32 v94, v85
	v_ldexp_f32 v158, v158, v159
	v_cndmask_b32_e32 v158, 0, v158, vcc
	v_cmp_nlt_f32_e32 vcc, s29, v96
	v_sub_f32_e32 v96, v165, v135
	v_add_f32_e32 v96, v139, v96
	v_sub_f32_e32 v96, v96, v164
	v_mul_f32_e32 v159, 0x3fb8aa3b, v96
	v_fma_f32 v160, v96, s0, -v159
	v_rndne_f32_e32 v161, v159
	v_fmac_f32_e32 v160, 0x32a5705f, v96
	v_sub_f32_e32 v159, v159, v161
	v_add_f32_e32 v159, v159, v160
	v_exp_f32_e32 v159, v159
	v_cvt_i32_f32_e32 v160, v161
	v_cndmask_b32_e32 v158, v229, v158, vcc
	v_cmp_ngt_f32_e32 vcc, s28, v96
	v_mov_b32_e32 v161, v88
	v_ldexp_f32 v159, v159, v160
	v_cndmask_b32_e32 v159, 0, v159, vcc
	v_cmp_nlt_f32_e32 vcc, s29, v96
	v_mov_b32_e32 v88, v93
	v_lshlrev_b32_e32 v96, 3, v170
	v_cndmask_b32_e32 v159, v229, v159, vcc
	v_mov_b32_e32 v160, v92
	v_pk_mul_f32 v[88:89], v[156:157], v[88:89]
	v_pk_mul_f32 v[160:161], v[156:157], v[160:161]
	v_pk_mul_f32 v[162:163], v[158:159], v[162:163]
	v_add3_u32 v92, 0, v96, v84
	v_cvt_pk_bf16_f32 v84, v88, v89
	v_pk_mul_f32 v[88:89], v[158:159], v[94:95]
	v_cvt_pk_bf16_f32 v160, v160, v161
	v_cvt_pk_bf16_f32 v161, v162, v163
	v_cvt_pk_bf16_f32 v85, v88, v89
	v_add_u32_e32 v92, 0x4000, v92
	ds_write2_b64 v92, v[160:161], v[84:85] offset1:18
	v_mov_b32_e32 v84, v90
	v_mov_b32_e32 v85, v86
	v_mov_b32_e32 v88, v82
	v_mov_b32_e32 v89, v80
	v_mov_b32_e32 v86, v91
	v_mov_b32_e32 v80, v83
	v_pk_mul_f32 v[84:85], v[156:157], v[84:85]
	v_pk_mul_f32 v[88:89], v[158:159], v[88:89]
	v_pk_mul_f32 v[86:87], v[156:157], v[86:87]
	v_pk_mul_f32 v[80:81], v[158:159], v[80:81]
	v_cvt_pk_bf16_f32 v84, v84, v85
	v_cvt_pk_bf16_f32 v85, v88, v89
	v_cvt_pk_bf16_f32 v82, v86, v87
	v_cvt_pk_bf16_f32 v83, v80, v81
	ds_write2_b64 v92, v[84:85], v[82:83] offset0:36 offset1:54
	v_mov_b32_e32 v80, v78
	v_mov_b32_e32 v81, v76
	v_mov_b32_e32 v82, v74
	v_mov_b32_e32 v83, v72
	v_mov_b32_e32 v76, v79
	v_mov_b32_e32 v72, v75
	v_pk_mul_f32 v[80:81], v[156:157], v[80:81]
	v_pk_mul_f32 v[82:83], v[158:159], v[82:83]
	v_pk_mul_f32 v[76:77], v[156:157], v[76:77]
	v_pk_mul_f32 v[72:73], v[158:159], v[72:73]
	v_cvt_pk_bf16_f32 v80, v80, v81
	v_cvt_pk_bf16_f32 v81, v82, v83
	v_cvt_pk_bf16_f32 v74, v76, v77
	v_cvt_pk_bf16_f32 v75, v72, v73
	ds_write2_b64 v92, v[80:81], v[74:75] offset0:72 offset1:90
	v_mov_b32_e32 v72, v70
	v_mov_b32_e32 v73, v68
	v_mov_b32_e32 v74, v66
	v_mov_b32_e32 v75, v64
	v_mov_b32_e32 v68, v71
	v_mov_b32_e32 v64, v67
	v_pk_mul_f32 v[72:73], v[156:157], v[72:73]
	v_pk_mul_f32 v[74:75], v[158:159], v[74:75]
	v_pk_mul_f32 v[68:69], v[156:157], v[68:69]
	v_pk_mul_f32 v[64:65], v[158:159], v[64:65]
	v_cvt_pk_bf16_f32 v72, v72, v73
	v_cvt_pk_bf16_f32 v73, v74, v75
	v_cvt_pk_bf16_f32 v66, v68, v69
	v_cvt_pk_bf16_f32 v67, v64, v65
	ds_write2_b64 v92, v[72:73], v[66:67] offset0:108 offset1:126
.LBB0_215:
	s_or_b64 exec, exec, s[12:13]
	v_lshlrev_b32_e32 v64, 4, v214
	v_and_b32_e32 v64, 0x70, v64
	v_add_u32_e32 v70, 0, v64
	v_ashrrev_i32_e32 v68, 3, v214
	v_mad_u64_u32 v[64:65], s[12:13], v68, s93, v[70:71]
	s_waitcnt vmcnt(0)
	ds_write_b128 v64, v[128:131] offset:53248
	v_add_u32_e32 v64, 0x200, v214
	v_ashrrev_i32_e32 v65, 3, v64
	v_mad_u64_u32 v[66:67], s[12:13], v65, s93, v[70:71]
	v_add_u32_e32 v64, 0x400, v214
	ds_write_b128 v66, v[140:143] offset:53248
	v_ashrrev_i32_e32 v66, 3, v64
	v_add_u32_e32 v64, 0x600, v214
	v_ashrrev_i32_e32 v64, 3, v64
	v_mad_u64_u32 v[72:73], s[12:13], v66, s93, v[70:71]
	v_mad_u64_u32 v[70:71], s[12:13], v64, s93, v[70:71]
	v_cmp_gt_i32_e32 vcc, 64, v214
	ds_write_b128 v72, v[144:147] offset:53248
	ds_write_b128 v70, v[148:151] offset:53248
	s_and_saveexec_b64 s[12:13], vcc
	v_lshl_add_u32 v67, v214, 2, 0
	v_add_u32_e32 v67, 0x20e00, v67
	ds_write_b32 v67, v97
	s_or_b64 exec, exec, s[12:13]
	s_cmpk_eq_i32 s82, 0x7c0
	v_and_b32_e32 v69, 7, v214
	s_cbranch_scc1 .LBB0_222
	v_lshlrev_b32_e32 v67, 2, v170
	s_add_i32 s12, s18, s82
	v_lshl_add_u32 v70, v169, 1, s8
	v_add_u32_e32 v71, s12, v67
	v_lshl_add_u32 v70, v71, 11, v70
	v_subrev_u32_e32 v70, s74, v70
	v_add_u32_e32 v71, 0x1e000, v70
	v_add_u32_e32 v72, 0x1f000, v70
	v_mov_b32_e32 v104, v71
	v_mov_b32_e32 v100, v72
	v_add_u32_e32 v71, 0x20000, v70
	s_add_i32 s12, s74, s57
	v_mov_b32_e32 v108, v72
	v_mov_b32_e32 v112, v71
	v_add_u32_e32 v70, 0x21000, v70
	v_mov_b32_e32 v116, v71
	v_mov_b32_e32 v120, v70
	v_lshl_add_u32 v71, v69, 4, s12
	v_add_u32_e32 v65, s62, v65
	v_add_u32_e32 v64, s62, v64
	v_add_u32_e32 v72, s62, v68
	v_lshl_add_u32 v65, v65, 16, v71
	v_add_u32_e32 v66, s62, v66
	v_lshl_add_u32 v64, v64, 16, v71
	v_lshl_add_u32 v72, v72, 16, v71
	v_subrev_u32_e32 v65, s74, v65
	v_lshl_add_u32 v66, v66, 16, v71
	v_subrev_u32_e32 v64, s74, v64
	v_subrev_u32_e32 v72, s74, v72
	v_mov_b32_e32 v124, v70
	v_mov_b32_e32 v128, v72
	v_subrev_u32_e32 v66, s74, v66
	v_mov_b32_e32 v140, v65
	v_mov_b32_e32 v144, v66
	v_mov_b32_e32 v148, v64
	s_and_saveexec_b64 s[12:13], s[44:45]
	s_cbranch_execz .LBB0_220
	s_add_i32 s15, s74, s88
	s_add_i32 s44, s15, 0x1f000400
	v_lshlrev_b32_e32 v64, 2, v67
	v_add_u32_e32 v65, s44, v64
	s_add_i32 s15, s15, 0x1f000700
	v_subrev_u32_e32 v65, s74, v65
	v_add_u32_e32 v64, s15, v64
	v_subrev_u32_e32 v64, s74, v64
	buffer_load_dwordx4 v[132:135], v65, s[76:79], 0 offen sc1
	buffer_load_dwordx4 v[136:139], v64, s[76:79], 0 offen sc1

.LBB0_266:
	s_or_b64 exec, exec, s[12:13]
	s_add_u32 s12, s74, s4
	s_addc_u32 s13, s75, s31
	s_waitcnt lgkmcnt(0)
	v_lshl_add_u64 v[64:65], s[12:13], 0, v[96:97]
	v_add_co_u32_e32 v66, vcc, 0xf000000, v64
	s_waitcnt lgkmcnt(0)
	s_barrier
	v_lshrrev_b32_e32 v218, 5, v168
	s_nop 0
	v_addc_co_u32_e32 v67, vcc, 0, v65, vcc
	global_load_dwordx2 v[206:207], v[66:67], off sc1
	global_load_dwordx2 v[204:205], v[66:67], off offset:2048 sc1
	v_add_co_u32_e32 v66, vcc, 0xf001000, v64
	v_lshlrev_b32_e32 v217, 4, v218
	s_nop 0
	v_addc_co_u32_e32 v67, vcc, 0, v65, vcc
	global_load_dwordx2 v[202:203], v[66:67], off sc1
	global_load_dwordx2 v[200:201], v[66:67], off offset:2048 sc1
	v_add_co_u32_e32 v66, vcc, 0xf002000, v64
	v_add_u32_e32 v208, 0, v217
	s_nop 0
	v_addc_co_u32_e32 v67, vcc, 0, v65, vcc
	v_add_co_u32_e32 v64, vcc, 0xf003000, v64
	global_load_dwordx2 v[198:199], v[66:67], off sc1
	global_load_dwordx2 v[196:197], v[66:67], off offset:2048 sc1
	v_addc_co_u32_e32 v65, vcc, 0, v65, vcc
	global_load_dwordx2 v[194:195], v[64:65], off sc1
	global_load_dwordx2 v[192:193], v[64:65], off offset:2048 sc1
	v_lshlrev_b32_e32 v64, 4, v168
	global_load_dwordx4 v[152:155], v64, s[50:51]
	v_mov_b32_e32 v64, s10
	ds_read_b32 v96, v64
	v_or_b32_e32 v64, s11, v215
	v_lshlrev_b32_e32 v68, 3, v218
	v_mul_u32_u24_e32 v69, 0x110, v215
	v_mad_u64_u32 v[64:65], s[12:13], v64, s93, v[208:209]
	v_add3_u32 v176, 0, v68, v69
	ds_read_b128 v[168:171], v64 offset:53248
	ds_read_b128 v[164:167], v64 offset:53280
	ds_read_b128 v[160:163], v64 offset:53312
	ds_read_b128 v[156:159], v64 offset:53344
	v_add_u32_e32 v177, 0x2000, v176
	s_add_i32 s12, 0, 0x20b00
	v_add_u32_e32 v220, s12, v217
	v_add_u32_e32 v219, s15, v217
	s_add_i32 s13, 0, 0x20d00
	s_add_i32 s15, 0, 0x20e00
	s_add_i32 s42, 0, 0x20f00
	s_movk_i32 s43, 0x840
	v_or_b32_e32 v216, 32, v215
	ds_read2_b64 v[232:235], v176 offset0:0 offset1:2
	ds_read2_b64 v[236:239], v177 offset0:64 offset1:66
	ds_read2_b64 v[240:243], v176 offset0:4 offset1:6
	ds_read2_b64 v[180:183], v177 offset0:68 offset1:70
	v_cvt_pk_bf16_f32 v172, v0, v1
	v_cvt_pk_bf16_f32 v173, v2, v3
	v_cvt_pk_bf16_f32 v174, v4, v5
	v_cvt_pk_bf16_f32 v175, v6, v7
	s_nop 0
	s_waitcnt lgkmcnt(3)
	v_mfma_f32_32x32x16_bf16 v[80:95], v[232:235], v[172:175], 0
	ds_read2_b64 v[232:235], v176 offset0:8 offset1:10
	s_waitcnt lgkmcnt(3)
	v_mfma_f32_32x32x16_bf16 v[64:79], v[236:239], v[172:175], 0
	ds_read2_b64 v[236:239], v177 offset0:72 offset1:74
	v_cvt_pk_bf16_f32 v244, v8, v9
	v_cvt_pk_bf16_f32 v245, v10, v11
	v_cvt_pk_bf16_f32 v246, v12, v13
	v_cvt_pk_bf16_f32 v247, v14, v15
	v_pk_mul_f32 v[0:1], v[0:1], v[96:97] op_sel_hi:[1,0]
	v_pk_mul_f32 v[2:3], v[2:3], v[96:97] op_sel_hi:[1,0]
	v_pk_mul_f32 v[4:5], v[4:5], v[96:97] op_sel_hi:[1,0]
	v_pk_mul_f32 v[6:7], v[6:7], v[96:97] op_sel_hi:[1,0]
	s_waitcnt lgkmcnt(3)
	v_mfma_f32_32x32x16_bf16 v[80:95], v[240:243], v[244:247], v[80:95]
	ds_read2_b64 v[240:243], v176 offset0:12 offset1:14
	s_waitcnt lgkmcnt(3)
	v_mfma_f32_32x32x16_bf16 v[64:79], v[180:183], v[244:247], v[64:79]
	ds_read2_b64 v[180:183], v177 offset0:76 offset1:78
	v_cvt_pk_bf16_f32 v172, v16, v17
	v_cvt_pk_bf16_f32 v173, v18, v19
	v_cvt_pk_bf16_f32 v174, v20, v21
	v_cvt_pk_bf16_f32 v175, v22, v23
	v_pk_mul_f32 v[8:9], v[8:9], v[96:97] op_sel_hi:[1,0]
	v_pk_mul_f32 v[10:11], v[10:11], v[96:97] op_sel_hi:[1,0]
	v_pk_mul_f32 v[12:13], v[12:13], v[96:97] op_sel_hi:[1,0]
	v_pk_mul_f32 v[14:15], v[14:15], v[96:97] op_sel_hi:[1,0]
	s_waitcnt lgkmcnt(3)
	v_mfma_f32_32x32x16_bf16 v[80:95], v[232:235], v[172:175], v[80:95]
	ds_read2_b64 v[232:235], v176 offset0:16 offset1:18
	s_waitcnt lgkmcnt(3)
	v_mfma_f32_32x32x16_bf16 v[64:79], v[236:239], v[172:175], v[64:79]
	ds_read2_b64 v[236:239], v177 offset0:80 offset1:82
	v_cvt_pk_bf16_f32 v244, v24, v25
	v_cvt_pk_bf16_f32 v245, v26, v27
	v_cvt_pk_bf16_f32 v246, v28, v29
	v_cvt_pk_bf16_f32 v247, v30, v31
	v_pk_mul_f32 v[16:17], v[16:17], v[96:97] op_sel_hi:[1,0]
	v_pk_mul_f32 v[18:19], v[18:19], v[96:97] op_sel_hi:[1,0]
	v_pk_mul_f32 v[20:21], v[20:21], v[96:97] op_sel_hi:[1,0]
	v_pk_mul_f32 v[22:23], v[22:23], v[96:97] op_sel_hi:[1,0]
	s_waitcnt lgkmcnt(3)
	v_mfma_f32_32x32x16_bf16 v[80:95], v[240:243], v[244:247], v[80:95]
	ds_read2_b64 v[240:243], v176 offset0:20 offset1:22
	s_waitcnt lgkmcnt(3)
	v_mfma_f32_32x32x16_bf16 v[64:79], v[180:183], v[244:247], v[64:79]
	ds_read2_b64 v[180:183], v177 offset0:84 offset1:86
	s_cmpk_eq_i32 s82, 0x7c0
	s_cbranch_scc1 .Lmls_0
	buffer_load_dwordx4 v[104:107], v104, s[76:79], 0 offen offset:2048 sc1
.Lmls_0:
	v_cvt_pk_bf16_f32 v172, v32, v33
	v_cvt_pk_bf16_f32 v173, v34, v35
	v_cvt_pk_bf16_f32 v174, v36, v37
	v_cvt_pk_bf16_f32 v175, v38, v39
	v_pk_mul_f32 v[24:25], v[24:25], v[96:97] op_sel_hi:[1,0]
	v_pk_mul_f32 v[26:27], v[26:27], v[96:97] op_sel_hi:[1,0]
	v_pk_mul_f32 v[28:29], v[28:29], v[96:97] op_sel_hi:[1,0]
	v_pk_mul_f32 v[30:31], v[30:31], v[96:97] op_sel_hi:[1,0]
	s_waitcnt lgkmcnt(3)
	v_mfma_f32_32x32x16_bf16 v[80:95], v[232:235], v[172:175], v[80:95]
	ds_read2_b64 v[232:235], v176 offset0:24 offset1:26
	s_waitcnt lgkmcnt(3)
	v_mfma_f32_32x32x16_bf16 v[64:79], v[236:239], v[172:175], v[64:79]
	ds_read2_b64 v[236:239], v177 offset0:88 offset1:90
	v_cvt_pk_bf16_f32 v244, v40, v41
	v_cvt_pk_bf16_f32 v245, v42, v43
	v_cvt_pk_bf16_f32 v246, v44, v45
	v_cvt_pk_bf16_f32 v247, v46, v47
	v_pk_mul_f32 v[32:33], v[32:33], v[96:97] op_sel_hi:[1,0]
	v_pk_mul_f32 v[34:35], v[34:35], v[96:97] op_sel_hi:[1,0]
	v_pk_mul_f32 v[36:37], v[36:37], v[96:97] op_sel_hi:[1,0]
	v_pk_mul_f32 v[38:39], v[38:39], v[96:97] op_sel_hi:[1,0]
	s_waitcnt lgkmcnt(3)
	v_mfma_f32_32x32x16_bf16 v[80:95], v[240:243], v[244:247], v[80:95]
	ds_read2_b64 v[240:243], v176 offset0:28 offset1:30
	s_waitcnt lgkmcnt(3)
	v_mfma_f32_32x32x16_bf16 v[64:79], v[180:183], v[244:247], v[64:79]
	ds_read2_b64 v[180:183], v177 offset0:92 offset1:94
	s_cmpk_eq_i32 s82, 0x7c0
	s_cbranch_scc1 .Lmls_1
	buffer_load_dwordx4 v[100:103], v100, s[76:79], 0 offen sc1
.Lmls_1:
	v_cvt_pk_bf16_f32 v172, v48, v49
	v_cvt_pk_bf16_f32 v173, v50, v51
	v_cvt_pk_bf16_f32 v174, v52, v53
	v_cvt_pk_bf16_f32 v175, v54, v55
	v_pk_mul_f32 v[40:41], v[40:41], v[96:97] op_sel_hi:[1,0]
	v_pk_mul_f32 v[42:43], v[42:43], v[96:97] op_sel_hi:[1,0]
	v_pk_mul_f32 v[44:45], v[44:45], v[96:97] op_sel_hi:[1,0]
	v_pk_mul_f32 v[46:47], v[46:47], v[96:97] op_sel_hi:[1,0]
	s_waitcnt lgkmcnt(3)
	v_mfma_f32_32x32x16_bf16 v[80:95], v[232:235], v[172:175], v[80:95]
	s_waitcnt lgkmcnt(2)
	v_mfma_f32_32x32x16_bf16 v[64:79], v[236:239], v[172:175], v[64:79]
	v_cvt_pk_bf16_f32 v244, v56, v57
	v_cvt_pk_bf16_f32 v245, v58, v59
	v_cvt_pk_bf16_f32 v246, v60, v61
	v_cvt_pk_bf16_f32 v247, v62, v63
	v_pk_mul_f32 v[48:49], v[48:49], v[96:97] op_sel_hi:[1,0]
	v_pk_mul_f32 v[50:51], v[50:51], v[96:97] op_sel_hi:[1,0]
	v_pk_mul_f32 v[52:53], v[52:53], v[96:97] op_sel_hi:[1,0]
	v_pk_mul_f32 v[54:55], v[54:55], v[96:97] op_sel_hi:[1,0]
	s_waitcnt lgkmcnt(1)
	v_mfma_f32_32x32x16_bf16 v[80:95], v[240:243], v[244:247], v[80:95]
	v_pk_mul_f32 v[56:57], v[56:57], v[96:97] op_sel_hi:[1,0]
	v_pk_mul_f32 v[58:59], v[58:59], v[96:97] op_sel_hi:[1,0]
	v_pk_mul_f32 v[60:61], v[60:61], v[96:97] op_sel_hi:[1,0]
	v_pk_mul_f32 v[62:63], v[62:63], v[96:97] op_sel_hi:[1,0]
	v_lshl_add_u32 v176, v215, 1, s2
	v_mad_u32_u24 v177, v215, s93, v219
	s_waitcnt lgkmcnt(0)
	v_mfma_f32_32x32x16_bf16 v[64:79], v[180:183], v[244:247], v[64:79]
	s_cmpk_eq_i32 s82, 0x7c0
	s_cbranch_scc1 .Lmls_2
	buffer_load_dwordx4 v[108:111], v108, s[76:79], 0 offen offset:2048 sc1
.Lmls_2:
	ds_read_b128 v[172:175], v220
	ds_read_b128 v[232:235], v220 offset:32
	ds_read_b128 v[236:239], v220 offset:64
	ds_read_b128 v[240:243], v220 offset:96
	s_waitcnt lgkmcnt(3)
	v_pk_mul_f32 v[82:83], v[82:83], v[174:175]
	s_waitcnt lgkmcnt(2)
	v_pk_mul_f32 v[86:87], v[86:87], v[234:235]
	s_waitcnt lgkmcnt(1)
	v_pk_mul_f32 v[90:91], v[90:91], v[238:239]
	v_pk_mul_f32 v[88:89], v[88:89], v[236:237]
	v_pk_mul_f32 v[84:85], v[84:85], v[232:233]
	ds_read_b128 v[232:235], v177
	ds_read_b128 v[236:239], v177 offset:32
	s_waitcnt lgkmcnt(2)
	v_pk_mul_f32 v[94:95], v[94:95], v[242:243]
	v_pk_mul_f32 v[92:93], v[92:93], v[240:241]
	v_pk_mul_f32 v[80:81], v[80:81], v[172:173]
	s_waitcnt lgkmcnt(1)
	s_nop 0
	v_mfma_f32_32x32x16_bf16 v[80:95], v[232:235], v[168:171], v[80:95]
	ds_read_b128 v[232:235], v177 offset:64
	s_waitcnt lgkmcnt(1)
	v_mfma_f32_32x32x16_bf16 v[80:95], v[236:239], v[164:167], v[80:95]
	s_waitcnt lgkmcnt(0)
	v_mfma_f32_32x32x16_bf16 v[80:95], v[232:235], v[160:163], v[80:95]
	ds_read_b128 v[232:235], v177 offset:96
	v_add_u32_e32 v177, s13, v217
	s_waitcnt lgkmcnt(0)
	v_mfma_f32_32x32x16_bf16 v[80:95], v[232:235], v[156:159], v[80:95]
	s_cmpk_eq_i32 s82, 0x7c0
	s_cbranch_scc1 .Lmls_3
	buffer_load_dwordx4 v[112:115], v112, s[76:79], 0 offen sc1
.Lmls_3:
	ds_read_b128 v[232:235], v177
	v_add_u32_e32 v177, s15, v217
	ds_read_b128 v[236:239], v177
	v_add_u32_e32 v177, s42, v217
	ds_read_b128 v[240:243], v177
	s_waitcnt lgkmcnt(1)
	v_fma_f32 v172, v172, v232, v236
	v_fmac_f32_e32 v239, v175, v235
	s_waitcnt lgkmcnt(0)
	v_max_f32_e32 v177, v240, v240
	v_max_f32_e64 v172, |v172|, v177
	v_rcp_f32_e32 v172, v172
	s_nop 0
	v_mul_f32_e32 v80, v80, v172
	v_cvt_pk_bf16_f32 v172, v80, s0
	v_mad_u32_u24 v80, v218, s43, v176
	ds_write_b16 v80, v172
	v_fma_f32 v172, v173, v233, v237
	v_max_f32_e32 v173, v241, v241
	v_max_f32_e64 v172, |v172|, v173
	v_rcp_f32_e32 v172, v172
	s_nop 0
	v_mul_f32_e32 v81, v81, v172
	v_cvt_pk_bf16_f32 v81, v81, s0
	ds_write_b16 v80, v81 offset:528
	v_fma_f32 v81, v174, v234, v238
	v_max_f32_e32 v172, v242, v242
	v_max_f32_e64 v81, |v81|, v172
	v_rcp_f32_e32 v81, v81
	s_nop 0
	v_mul_f32_e32 v81, v82, v81
	v_cvt_pk_bf16_f32 v81, v81, s0
	ds_write_b16 v80, v81 offset:1056
	v_max_f32_e32 v81, v243, v243
	v_max_f32_e64 v81, |v239|, v81
	v_rcp_f32_e32 v81, v81
	s_nop 0
	v_mul_f32_e32 v81, v83, v81
	v_cvt_pk_bf16_f32 v81, v81, s0
	ds_write_b16 v80, v81 offset:1584
	s_cmpk_eq_i32 s82, 0x7c0
	s_cbranch_scc1 .Lmls_4
	buffer_load_dwordx4 v[116:119], v116, s[76:79], 0 offen offset:2048 sc1
.Lmls_4:
	v_lshl_or_b32 v81, v218, 2, 8
	v_lshlrev_b32_e32 v82, 2, v81
	v_add_u32_e32 v83, s12, v82
	ds_read_b128 v[172:175], v83
	v_add_u32_e32 v83, s13, v82
	ds_read_b128 v[232:235], v83
	v_add_u32_e32 v83, s15, v82
	v_add_u32_e32 v82, s42, v82
	ds_read_b128 v[236:239], v83
	ds_read_b128 v[240:243], v82
	v_mad_u32_u24 v81, v81, s85, v176
	s_waitcnt lgkmcnt(1)
	v_fma_f32 v82, v172, v232, v236
	s_waitcnt lgkmcnt(0)
	v_max_f32_e32 v83, v240, v240
	v_max_f32_e64 v82, |v82|, v83
	v_rcp_f32_e32 v82, v82
	v_max_f32_e32 v83, v241, v241
	v_fmac_f32_e32 v239, v175, v235
	v_mul_f32_e32 v82, v84, v82
	v_cvt_pk_bf16_f32 v82, v82, s0
	ds_write_b16 v81, v82
	v_fma_f32 v82, v173, v233, v237
	v_max_f32_e64 v82, |v82|, v83
	v_rcp_f32_e32 v82, v82
	v_max_f32_e32 v83, v242, v242
	v_mul_f32_e32 v82, v85, v82
	v_cvt_pk_bf16_f32 v82, v82, s0
	ds_write_b16 v80, v82 offset:4752
	v_fma_f32 v82, v174, v234, v238
	v_max_f32_e64 v82, |v82|, v83
	v_rcp_f32_e32 v82, v82
	s_nop 0
	v_mul_f32_e32 v82, v86, v82
	v_cvt_pk_bf16_f32 v82, v82, s0
	ds_write_b16 v80, v82 offset:5280
	v_max_f32_e32 v82, v243, v243
	v_max_f32_e64 v82, |v239|, v82
	v_rcp_f32_e32 v82, v82
	v_or_b32_e32 v86, 64, v217
	v_mul_f32_e32 v82, v87, v82
	v_cvt_pk_bf16_f32 v82, v82, s0
	ds_write_b16 v80, v82 offset:5808
	s_cmpk_eq_i32 s82, 0x7c0
	s_cbranch_scc1 .Lmls_5
	buffer_load_dwordx4 v[120:123], v120, s[76:79], 0 offen sc1
.Lmls_5:
	v_add_u32_e32 v87, s13, v86
	v_add_u32_e32 v82, s12, v86
	ds_read_b128 v[172:175], v87
	v_add_u32_e32 v87, s15, v86
	v_add_u32_e32 v86, s42, v86
	ds_read_b128 v[82:85], v82
	ds_read_b128 v[236:239], v86
	ds_read_b128 v[232:235], v87
	s_waitcnt lgkmcnt(1)
	v_max_f32_e32 v86, v236, v236
	s_waitcnt lgkmcnt(0)
	v_fma_f32 v82, v82, v172, v232
	v_max_f32_e64 v82, |v82|, v86
	v_rcp_f32_e32 v82, v82
	v_fmac_f32_e32 v235, v85, v175
	v_mul_f32_e32 v82, v88, v82
	v_cvt_pk_bf16_f32 v82, v82, s0
	ds_write_b16 v81, v82 offset:4224
	v_fma_f32 v82, v83, v173, v233
	v_max_f32_e32 v83, v237, v237
	v_max_f32_e64 v82, |v82|, v83
	v_rcp_f32_e32 v82, v82
	v_max_f32_e32 v83, v238, v238
	v_mul_f32_e32 v82, v89, v82
	v_cvt_pk_bf16_f32 v82, v82, s0
	ds_write_b16 v80, v82 offset:8976
	v_fma_f32 v82, v84, v174, v234
	v_max_f32_e64 v82, |v82|, v83
	v_rcp_f32_e32 v82, v82
	s_nop 0
	v_mul_f32_e32 v82, v90, v82
	v_cvt_pk_bf16_f32 v82, v82, s0
	ds_write_b16 v80, v82 offset:9504
	v_max_f32_e32 v82, v239, v239
	v_max_f32_e64 v82, |v235|, v82
	v_rcp_f32_e32 v82, v82
	v_or_b32_e32 v90, 0x60, v217
	v_add_u32_e32 v86, s13, v90
	v_mul_f32_e32 v82, v91, v82
	v_cvt_pk_bf16_f32 v82, v82, s0
	ds_write_b16 v80, v82 offset:10032
	s_cmpk_eq_i32 s82, 0x7c0
	s_cbranch_scc1 .Lmls_6
	buffer_load_dwordx4 v[124:127], v124, s[76:79], 0 offen offset:2048 sc1
.Lmls_6:
	v_add_u32_e32 v82, s12, v90
	v_add_u32_e32 v91, s15, v90
	v_add_u32_e32 v90, s42, v90
	ds_read_b128 v[82:85], v82
	ds_read_b128 v[86:89], v86
	ds_read_b128 v[172:175], v91
	ds_read_b128 v[232:235], v90
	s_waitcnt lgkmcnt(1)
	v_fma_f32 v82, v82, v86, v172
	s_waitcnt lgkmcnt(0)
	v_max_f32_e32 v86, v232, v232
	v_max_f32_e64 v82, |v82|, v86
	v_rcp_f32_e32 v82, v82
	v_fmac_f32_e32 v175, v85, v89
	v_mul_f32_e32 v82, v92, v82
	v_cvt_pk_bf16_f32 v82, v82, s0
	ds_write_b16 v81, v82 offset:8448
	v_fma_f32 v82, v83, v87, v173
	v_max_f32_e32 v83, v233, v233
	v_max_f32_e64 v82, |v82|, v83
	v_rcp_f32_e32 v82, v82
	v_max_f32_e32 v83, v234, v234
	v_mul_f32_e32 v82, v93, v82
	v_cvt_pk_bf16_f32 v82, v82, s0
	ds_write_b16 v80, v82 offset:13200
	v_fma_f32 v82, v84, v88, v174
	v_max_f32_e64 v82, |v82|, v83
	v_rcp_f32_e32 v82, v82
	s_nop 0
	v_mul_f32_e32 v82, v94, v82
	v_cvt_pk_bf16_f32 v82, v82, s0
	ds_write_b16 v80, v82 offset:13728
	v_max_f32_e32 v82, v235, v235
	v_max_f32_e64 v82, |v175|, v82
	v_rcp_f32_e32 v82, v82
	v_mad_u32_u24 v94, v216, s93, v219
	v_mul_f32_e32 v82, v95, v82
	v_cvt_pk_bf16_f32 v82, v82, s0
	ds_write_b16 v80, v82 offset:14256
	s_cmpk_eq_i32 s82, 0x7c0
	s_cbranch_scc1 .Lmls_7
	buffer_load_dwordx4 v[128:131], v128, s[76:79], 0 offen sc1
.Lmls_7:
	ds_read_b128 v[82:85], v220 offset:128
	ds_read_b128 v[86:89], v220 offset:160
	ds_read_b128 v[90:93], v220 offset:192
	ds_read_b128 v[172:175], v220 offset:224
	s_waitcnt lgkmcnt(3)
	v_pk_mul_f32 v[66:67], v[66:67], v[84:85]
	s_waitcnt lgkmcnt(2)
	v_pk_mul_f32 v[68:69], v[68:69], v[86:87]
	s_waitcnt lgkmcnt(1)
	v_pk_mul_f32 v[72:73], v[72:73], v[90:91]
	v_pk_mul_f32 v[74:75], v[74:75], v[92:93]
	v_pk_mul_f32 v[70:71], v[70:71], v[88:89]
	ds_read_b128 v[86:89], v94
	ds_read_b128 v[90:93], v94 offset:32
	s_waitcnt lgkmcnt(2)
	v_pk_mul_f32 v[76:77], v[76:77], v[172:173]
	v_pk_mul_f32 v[78:79], v[78:79], v[174:175]
	v_pk_mul_f32 v[64:65], v[64:65], v[82:83]
	s_waitcnt lgkmcnt(1)
	s_nop 0
	v_mfma_f32_32x32x16_bf16 v[64:79], v[86:89], v[168:171], v[64:79]
	ds_read_b128 v[86:89], v94 offset:64
	s_waitcnt lgkmcnt(1)
	v_mfma_f32_32x32x16_bf16 v[64:79], v[90:93], v[164:167], v[64:79]
	s_waitcnt lgkmcnt(0)
	v_mfma_f32_32x32x16_bf16 v[64:79], v[86:89], v[160:163], v[64:79]
	ds_read_b128 v[86:89], v94 offset:96
	v_or_b32_e32 v94, 0x80, v217
	v_add_u32_e32 v90, s15, v94
	ds_read_b128 v[90:93], v90
	s_waitcnt lgkmcnt(1)
	v_mfma_f32_32x32x16_bf16 v[64:79], v[86:89], v[156:159], v[64:79]
	s_cmpk_eq_i32 s82, 0x7c0
	s_cbranch_scc1 .Lmls_8
	buffer_load_dwordx4 v[140:143], v140, s[76:79], 0 offen sc1
.Lmls_8:
	v_add_u32_e32 v86, s13, v94
	v_add_u32_e32 v94, s42, v94
	ds_read_b128 v[86:89], v86
	ds_read_b128 v[172:175], v94
	s_waitcnt lgkmcnt(1)
	v_fma_f32 v82, v82, v86, v90
	s_waitcnt lgkmcnt(0)
	v_max_f32_e32 v86, v172, v172
	v_max_f32_e64 v82, |v82|, v86
	v_rcp_f32_e32 v82, v82
	v_fmac_f32_e32 v93, v85, v89
	v_or_b32_e32 v90, 0xa0, v217
	v_add_u32_e32 v86, s15, v90
	v_mul_f32_e32 v64, v64, v82
	v_cvt_pk_bf16_f32 v64, v64, s0
	ds_write_b16 v81, v64 offset:12672
	v_fma_f32 v64, v83, v87, v91
	v_max_f32_e32 v82, v173, v173
	v_max_f32_e64 v64, |v64|, v82
	v_rcp_f32_e32 v64, v64
	v_add_u32_e32 v82, s13, v90
	v_mul_f32_e32 v64, v65, v64
	v_cvt_pk_bf16_f32 v64, v64, s0
	ds_write_b16 v80, v64 offset:17424
	v_fma_f32 v64, v84, v88, v92
	v_max_f32_e32 v65, v174, v174
	v_max_f32_e64 v64, |v64|, v65
	v_rcp_f32_e32 v64, v64
	s_nop 0
	v_mul_f32_e32 v64, v66, v64
	v_cvt_pk_bf16_f32 v64, v64, s0
	ds_write_b16 v80, v64 offset:17952
	v_max_f32_e32 v64, v175, v175
	v_max_f32_e64 v64, |v93|, v64
	v_rcp_f32_e32 v64, v64
	s_nop 0
	v_mul_f32_e32 v64, v67, v64
	v_cvt_pk_bf16_f32 v64, v64, s0
	ds_write_b16 v80, v64 offset:18480
	s_cmpk_eq_i32 s82, 0x7c0
	s_cbranch_scc1 .Lmls_9
	buffer_load_dwordx4 v[144:147], v144, s[76:79], 0 offen sc1
.Lmls_9:
	v_add_u32_e32 v64, s12, v90
	v_add_u32_e32 v90, s42, v90
	ds_read_b128 v[64:67], v64
	ds_read_b128 v[82:85], v82
	ds_read_b128 v[86:89], v86
	ds_read_b128 v[90:93], v90
	s_waitcnt lgkmcnt(1)
	v_fma_f32 v64, v64, v82, v86
	s_waitcnt lgkmcnt(0)
	v_max_f32_e32 v82, v90, v90
	v_max_f32_e64 v64, |v64|, v82
	v_rcp_f32_e32 v64, v64
	v_fmac_f32_e32 v89, v67, v85
	v_or_b32_e32 v86, 0xc0, v217
	v_add_u32_e32 v82, s15, v86
	v_mul_f32_e32 v64, v68, v64
	v_cvt_pk_bf16_f32 v64, v64, s0
	ds_write_b16 v81, v64 offset:16896
	v_fma_f32 v64, v65, v83, v87
	v_max_f32_e32 v65, v91, v91
	v_max_f32_e64 v64, |v64|, v65
	v_rcp_f32_e32 v64, v64
	v_max_f32_e32 v65, v92, v92
	v_add_u32_e32 v68, s13, v86
	v_mul_f32_e32 v64, v69, v64
	v_cvt_pk_bf16_f32 v64, v64, s0
	ds_write_b16 v80, v64 offset:21648
	v_fma_f32 v64, v66, v84, v88
	v_max_f32_e64 v64, |v64|, v65
	v_rcp_f32_e32 v64, v64
	s_nop 0
	v_mul_f32_e32 v64, v70, v64
	v_cvt_pk_bf16_f32 v64, v64, s0
	ds_write_b16 v80, v64 offset:22176
	v_max_f32_e32 v64, v93, v93
	v_max_f32_e64 v64, |v89|, v64
	v_rcp_f32_e32 v64, v64
	s_nop 0
	v_mul_f32_e32 v64, v71, v64
	v_cvt_pk_bf16_f32 v64, v64, s0
	ds_write_b16 v80, v64 offset:22704
	s_cmpk_eq_i32 s82, 0x7c0
	s_cbranch_scc1 .Lmls_10
	buffer_load_dwordx4 v[148:151], v148, s[76:79], 0 offen sc1
.Lmls_10:
	v_add_u32_e32 v64, s12, v86
	v_add_u32_e32 v86, s42, v86
	ds_read_b128 v[64:67], v64
	ds_read_b128 v[68:71], v68
	ds_read_b128 v[82:85], v82
	ds_read_b128 v[86:89], v86
	s_waitcnt lgkmcnt(1)
	v_fma_f32 v64, v64, v68, v82
	s_waitcnt lgkmcnt(0)
	v_max_f32_e32 v68, v86, v86
	v_max_f32_e64 v64, |v64|, v68
	v_rcp_f32_e32 v64, v64
	v_fmac_f32_e32 v85, v67, v71
	v_or_b32_e32 v82, 0xe0, v217
	v_add_u32_e32 v68, s13, v82
	v_mul_f32_e32 v64, v72, v64
	v_cvt_pk_bf16_f32 v64, v64, s0
	ds_write_b16 v81, v64 offset:21120
	v_fma_f32 v64, v65, v69, v83
	v_max_f32_e32 v65, v87, v87
	v_max_f32_e64 v64, |v64|, v65
	v_rcp_f32_e32 v64, v64
	v_max_f32_e32 v65, v88, v88
	v_add_u32_e32 v72, s15, v82
	v_mul_f32_e32 v64, v73, v64
	v_cvt_pk_bf16_f32 v64, v64, s0
	ds_write_b16 v80, v64 offset:25872
	v_fma_f32 v64, v66, v70, v84
	v_max_f32_e64 v64, |v64|, v65
	v_rcp_f32_e32 v64, v64
	s_nop 0
	v_mul_f32_e32 v64, v74, v64
	v_cvt_pk_bf16_f32 v64, v64, s0
	ds_write_b16 v80, v64 offset:26400
	v_max_f32_e32 v64, v89, v89
	v_max_f32_e64 v64, |v85|, v64
	v_rcp_f32_e32 v64, v64
	s_nop 0
	v_mul_f32_e32 v64, v75, v64
	v_cvt_pk_bf16_f32 v64, v64, s0
	ds_write_b16 v80, v64 offset:26928
	v_add_u32_e32 v64, s12, v82
	v_add_u32_e32 v82, s42, v82
	ds_read_b128 v[64:67], v64
	ds_read_b128 v[68:71], v68
	ds_read_b128 v[72:75], v72
	ds_read_b128 v[82:85], v82
	s_waitcnt lgkmcnt(1)
	v_fma_f32 v64, v64, v68, v72
	s_waitcnt lgkmcnt(0)
	v_max_f32_e32 v68, v82, v82
	v_max_f32_e64 v64, |v64|, v68
	v_rcp_f32_e32 v64, v64
	v_fmac_f32_e32 v75, v67, v71
	v_mad_u32_u24 v72, v215, s93, v208
	v_mul_f32_e32 v64, v76, v64
	v_cvt_pk_bf16_f32 v64, v64, s0
	ds_write_b16 v81, v64 offset:25344
	v_fma_f32 v64, v65, v69, v73
	v_max_f32_e32 v65, v83, v83
	v_max_f32_e64 v64, |v64|, v65
	v_rcp_f32_e32 v64, v64
	v_max_f32_e32 v65, v84, v84
	v_mad_u32_u24 v73, v216, s93, v208
	v_mul_f32_e32 v64, v77, v64
	v_cvt_pk_bf16_f32 v64, v64, s0
	ds_write_b16 v80, v64 offset:30096
	v_fma_f32 v64, v66, v70, v74
	v_max_f32_e64 v64, |v64|, v65
	v_rcp_f32_e32 v64, v64
	v_and_b32_e32 v74, 3, v214
	v_cmp_eq_u32_e32 vcc, 0, v74
	v_mul_f32_e32 v64, v78, v64
	v_cvt_pk_bf16_f32 v64, v64, s0
	ds_write_b16 v80, v64 offset:30624
	v_max_f32_e32 v64, v85, v85
	v_max_f32_e64 v64, |v75|, v64
	v_rcp_f32_e32 v64, v64
	s_nop 0
	v_mul_f32_e32 v64, v79, v64
	v_cvt_pk_bf16_f32 v64, v64, s0
	ds_write_b16 v80, v64 offset:31152
	ds_read_b128 v[64:67], v72 offset:34816
	ds_read_b128 v[68:71], v72 offset:34848
	ds_read_b128 v[76:79], v72 offset:34880
	ds_read_b128 v[80:83], v72 offset:34912
	ds_read_b128 v[84:87], v73 offset:34816
	ds_read_b128 v[88:91], v73 offset:34848
	s_waitcnt lgkmcnt(5)
	v_mfma_f32_32x32x16_bf16 v[0:15], v[64:67], v[168:171], v[0:15]
	ds_read_b128 v[64:67], v73 offset:34880
	s_waitcnt lgkmcnt(5)
	v_mfma_f32_32x32x16_bf16 v[0:15], v[68:71], v[164:167], v[0:15]
	ds_read_b128 v[68:71], v73 offset:34912
	s_waitcnt lgkmcnt(5)
	v_mfma_f32_32x32x16_bf16 v[0:15], v[76:79], v[160:163], v[0:15]
	ds_read_b128 v[76:79], v72 offset:44032
	s_waitcnt lgkmcnt(5)
	v_mfma_f32_32x32x16_bf16 v[0:15], v[80:83], v[156:159], v[0:15]
	ds_read_b128 v[80:83], v72 offset:44064
	s_waitcnt lgkmcnt(5)
	v_mfma_f32_32x32x16_bf16 v[16:31], v[84:87], v[168:171], v[16:31]
	ds_read_b128 v[84:87], v72 offset:44096
	s_waitcnt lgkmcnt(5)
	v_mfma_f32_32x32x16_bf16 v[16:31], v[88:91], v[164:167], v[16:31]
	ds_read_b128 v[88:91], v72 offset:44128
	s_waitcnt lgkmcnt(5)
	v_mfma_f32_32x32x16_bf16 v[16:31], v[64:67], v[160:163], v[16:31]
	ds_read_b128 v[64:67], v72 offset:48640
	s_waitcnt lgkmcnt(5)
	v_mfma_f32_32x32x16_bf16 v[16:31], v[68:71], v[156:159], v[16:31]
	ds_read_b128 v[68:71], v72 offset:48672
	s_waitcnt lgkmcnt(5)
	v_mfma_f32_32x32x16_bf16 v[32:47], v[76:79], v[168:171], v[32:47]
	ds_read_b128 v[76:79], v72 offset:48704
	s_waitcnt lgkmcnt(5)
	v_mfma_f32_32x32x16_bf16 v[32:47], v[80:83], v[164:167], v[32:47]
	ds_read_b128 v[80:83], v72 offset:48736
	s_waitcnt lgkmcnt(5)
	v_mfma_f32_32x32x16_bf16 v[32:47], v[84:87], v[160:163], v[32:47]
	s_waitcnt lgkmcnt(4)
	v_mfma_f32_32x32x16_bf16 v[32:47], v[88:91], v[156:159], v[32:47]
	s_waitcnt lgkmcnt(3)
	v_mfma_f32_32x32x16_bf16 v[48:63], v[64:67], v[168:171], v[48:63]
	s_waitcnt lgkmcnt(2)
	v_mfma_f32_32x32x16_bf16 v[48:63], v[68:71], v[164:167], v[48:63]
	s_waitcnt lgkmcnt(1)
	v_mfma_f32_32x32x16_bf16 v[48:63], v[76:79], v[160:163], v[48:63]
	s_waitcnt lgkmcnt(0)
	v_mfma_f32_32x32x16_bf16 v[48:63], v[80:83], v[156:159], v[48:63]
	v_ashrrev_i32_e32 v64, 2, v214
	v_mul_lo_u32 v65, v64, s93
	v_lshlrev_b32_e32 v66, 5, v74
	v_add3_u32 v65, 0, v65, v66
	ds_read_b128 v[66:69], v65 offset:34816
	ds_read_b128 v[70:73], v65 offset:34832
	s_waitcnt lgkmcnt(1)
	v_lshlrev_b32_e32 v65, 16, v66
	v_and_b32_e32 v66, 0xffff0000, v66
	v_add_f32_e32 v65, v65, v66
	s_waitcnt lgkmcnt(0)
	v_lshlrev_b32_e32 v66, 16, v70
	v_and_b32_e32 v70, 0xffff0000, v70
	v_add_f32_e32 v66, v66, v70
	v_add_f32_e32 v65, v65, v66
	v_lshlrev_b32_e32 v66, 16, v67
	v_and_b32_e32 v67, 0xffff0000, v67
	v_add_f32_e32 v66, v66, v67
	v_lshlrev_b32_e32 v67, 16, v71
	v_and_b32_e32 v70, 0xffff0000, v71
	v_add_f32_e32 v67, v67, v70
	v_add_f32_e32 v65, 0, v65
	v_add_f32_e32 v66, v66, v67
	v_add_f32_e32 v65, v66, v65
	v_lshlrev_b32_e32 v66, 16, v68
	v_and_b32_e32 v67, 0xffff0000, v68
	v_add_f32_e32 v66, v66, v67
	v_lshlrev_b32_e32 v67, 16, v72
	v_and_b32_e32 v68, 0xffff0000, v72
	v_add_f32_e32 v67, v67, v68
	v_add_f32_e32 v66, v66, v67
	v_add_f32_e32 v65, v66, v65
	v_lshlrev_b32_e32 v66, 16, v69
	v_and_b32_e32 v67, 0xffff0000, v69
	v_add_f32_e32 v66, v66, v67
	v_lshlrev_b32_e32 v67, 16, v73
	v_and_b32_e32 v68, 0xffff0000, v73
	v_add_f32_e32 v67, v67, v68
	v_add_f32_e32 v66, v66, v67
	v_add_f32_e32 v65, v66, v65
	ds_bpermute_b32 v66, v189, v65
	s_waitcnt lgkmcnt(0)
	v_add_f32_e32 v65, v65, v66
	ds_bpermute_b32 v66, v191, v65
	s_and_saveexec_b64 s[12:13], vcc
	s_cbranch_execz .LBB0_206
	v_lshl_add_u32 v64, v64, 2, 0
	v_add_u32_e32 v64, 0x21000, v64
	s_waitcnt lgkmcnt(0)
	v_add_f32_e32 v65, v65, v66
	ds_read_b32 v66, v64
	s_waitcnt lgkmcnt(0)
	v_fmac_f32_e32 v65, v96, v66
	ds_write_b32 v64, v65
	s_branch .LBB0_206
